# barrier poll back-off: v92 with s_sleep 3 instead of s_sleep 1 in the 11 grid-barrier poll loops
# baseline (speedup 1.0000x reference)
.Lh2_spin_0:
	s_sleep 3
	global_load_dword v4, v2, s[100:101] sc1
	s_waitcnt vmcnt(0)
	v_cmp_lt_u32_e32 vcc, v4, v9
	s_cbranch_vccnz .Lh2_spin_0
	buffer_inv sc1
	s_waitcnt vmcnt(0)

.Lh2_spin_5:
	s_sleep 3
	global_load_dword v4, v2, s[100:101] sc1
	s_waitcnt vmcnt(0)
	v_cmp_lt_u32_e32 vcc, v4, v9
	s_cbranch_vccnz .Lh2_spin_5
	buffer_inv sc1
	s_waitcnt vmcnt(0)
	s_branch .LBB0_380

.Lf2_spin_b:
	s_sleep 3
	global_load_dword v234, v232, s[100:101] sc1
	s_waitcnt vmcnt(0)
	v_cmp_lt_u32_e32 vcc, v234, v239
	s_cbranch_vccnz .Lf2_spin_b
	buffer_inv sc1
	s_waitcnt vmcnt(0)
